# MLA loop: next-tile LDS staging moved back to the end of the step (after the PV MFMAs) keeping the early V reads
# speedup vs baseline: 1.0121x; 1.0088x over previous
; #define LAS __attribute__((address_space(3)))
; template <bool SUM> __device__ __forceinline__ bool softmax_tile(f32x16& pa, f32x16& pb, float& m, float& l, f32x16& o0, f32x16& o1, bool first) {
;     float rm;
;     if (first) { rm = fmaxf(max16(pa), max16(pb)); rm = fmaxf(rm, __shfl_xor(rm, 32)); }
;     else { int im = max(imax16(pa), imax16(pb));
;         const auto rr = __builtin_amdgcn_permlane32_swap((unsigned)im, (unsigned)im, false, false); im = max((int)rr[0], (int)rr[1]); rm = __int_as_float(im); }
;     bool moved = false;
;     if (first || __any(rm > 8.0f)) {
;         asm volatile("" ::: "memory");
;         const float dl = first ? rm : fmaxf(rm, 0.f); m += dl; moved = true;
;         if (!first) { const float f = __builtin_amdgcn_exp2f(-dl); l *= f;
; #pragma unroll
;             for (int r = 0; r < 16; ++r) { o0[r] *= f; o1[r] *= f; } }
; #pragma unroll
;         for (int r = 0; r < 16; ++r) { pa[r] -= dl; pb[r] -= dl; }
;     }
;     ...
; #pragma unroll
;                     for (int hf = 0; hf < 2; ++hf)
; #pragma unroll
;                         for (int d = 1; d < NQ; ++d) p[hf] = MFMA32(kf[0][hf][d], qr[d], p[hf]);
;                 }
;                 __builtin_amdgcn_sched_barrier(0);
;                 const float l_before = l[mp];
;                 const bool moved = softmax_tile<MODE == 1>(p[0], p[1], m[mp], l[mp], o[mp][0], o[mp][1], first_t);
;                 if constexpr (MODE == 1 && FAST) { if (moved) { unsigned h1, h2, h3; split3_bf16(-m[mp], h1, h2, h3);
;                         if (hi) { const u32x4 qv = {h1 | (h2 << 16), h3, 0u, 0u}; qx[mp] = __builtin_bit_cast(bf16x8, qv); } } }
;                 if (MODE == 0 && moved) { const float f = first_t ? 0.f : l[0] / l_before;
; #pragma unroll
;                     for (int r = 0; r < 16; ++r) { negm[r] = -m[0]; lsum[r] *= f; } l[0] = 1.0f; }
; #pragma unroll
;                 for (int ks = 0; ks < 4; ++ks) pf[mp][ks] = pack_frag(p[ks >> 1], ks & 1);
;             }
;             const LAS unsigned char* vb = bb + KB + r32 * VP + 8 * hi;
; #pragma unroll
;             for (int dh = 0; dh < 2; ++dh) {
;                 bf16x8 vf[4];
; #pragma unroll
;                 for (int ks = 0; ks < 4; ++ks) {
;                     const u32x2 v0 = *(const LAS u32x2*)(vb + dh * 32 * VP + 32 * ks), v1 = *(const LAS u32x2*)(vb + dh * 32 * VP + 32 * ks + 16);
.LBB0_264:
	s_waitcnt lgkmcnt(10)
	v_mfma_f32_32x32x16_bf16 v[68:83], v[172:175], v[108:111], v[68:83]
	s_waitcnt lgkmcnt(4)
	v_mfma_f32_32x32x16_bf16 v[84:99], v[152:155], v[108:111], v[84:99]
	v_mfma_f32_32x32x16_bf16 v[68:83], v[168:171], v[112:115], v[68:83]
	s_waitcnt lgkmcnt(3)
	v_mfma_f32_32x32x16_bf16 v[84:99], v[148:151], v[112:115], v[84:99]
	v_mfma_f32_32x32x16_bf16 v[68:83], v[164:167], v[116:119], v[68:83]
	s_waitcnt lgkmcnt(2)
	v_mfma_f32_32x32x16_bf16 v[84:99], v[144:147], v[116:119], v[84:99]
	v_mfma_f32_32x32x16_bf16 v[68:83], v[160:163], v[124:127], v[68:83]
	s_waitcnt lgkmcnt(1)
	v_mfma_f32_32x32x16_bf16 v[84:99], v[140:143], v[124:127], v[84:99]
	v_mfma_f32_32x32x16_bf16 v[68:83], v[156:159], v[120:123], v[68:83]
	s_waitcnt lgkmcnt(0)
	v_mfma_f32_32x32x16_bf16 v[84:99], v[136:139], v[120:123], v[84:99]
	v_add3_u32 v180, s15, v206, v199
	v_add_u32_e32 v181, 0x3000, v180
	v_add_u32_e32 v180, 0x4000, v180
	ds_read_b64 v[144:145], v181 offset:1024
	ds_read_b64 v[146:147], v181 offset:1040
	ds_read_b64 v[160:161], v180 offset:1280
	ds_read_b64 v[162:163], v180 offset:1296
	ds_read_b64 v[148:149], v181 offset:1056
	ds_read_b64 v[150:151], v181 offset:1072
	ds_read_b64 v[164:165], v180 offset:1312
	ds_read_b64 v[166:167], v180 offset:1328
	ds_read_b64 v[152:153], v181 offset:1088
	ds_read_b64 v[154:155], v181 offset:1104
	ds_read_b64 v[168:169], v180 offset:1344
	ds_read_b64 v[170:171], v180 offset:1360
	ds_read_b64 v[156:157], v181 offset:1120
	ds_read_b64 v[158:159], v181 offset:1136
	ds_read_b64 v[172:173], v180 offset:1376
	ds_read_b64 v[174:175], v180 offset:1392
	v_max3_i32 v136, v68, v69, v70
	v_max3_i32 v137, v71, v72, v73
	v_max3_i32 v138, v74, v75, v76
	v_max3_i32 v139, v77, v78, v79
	v_max3_i32 v140, v80, v81, v82
	v_max3_i32 v136, v136, v137, v138
	v_max3_i32 v137, v139, v140, v83
	v_max_i32_e32 v138, v84, v85
	v_max3_i32 v139, v87, v88, v89
	v_max3_i32 v141, v93, v94, v95
	v_max3_i32 v142, v96, v97, v98
	v_max3_i32 v140, v90, v91, v92
	v_max3_i32 v138, v138, v86, v139
	v_max3_i32 v139, v141, v142, v99
	v_max3_i32 v138, v138, v140, v139
	v_max3_i32 v136, v136, v137, v138
	v_mov_b32_e32 v137, v136
	s_nop 1
	v_permlane32_swap_b32_e32 v136, v137
	v_max_i32_e32 v136, v136, v137
	v_cmp_lt_f32_e32 vcc, s17, v136
	s_cmp_lg_u64 vcc, 0
	s_cselect_b64 s[46:47], -1, 0
	s_cbranch_vccz .LBB0_272
	v_max_f32_e32 v136, v136, v136
	v_max_f32_e32 v138, 0, v136
	v_exp_f32_e64 v140, -v138
	v_add_f32_e32 v207, v207, v138
	v_pk_add_f32 v[68:69], v[68:69], v[138:139] op_sel_hi:[1,0] neg_lo:[0,1] neg_hi:[0,1]
	v_mul_f32_e32 v136, v208, v140
	v_pk_mul_f32 v[34:35], v[34:35], v[140:141] op_sel_hi:[1,0]
	v_pk_mul_f32 v[32:33], v[32:33], v[140:141] op_sel_hi:[1,0]
	v_pk_mul_f32 v[30:31], v[30:31], v[140:141] op_sel_hi:[1,0]
	v_pk_mul_f32 v[28:29], v[28:29], v[140:141] op_sel_hi:[1,0]
	v_pk_mul_f32 v[26:27], v[26:27], v[140:141] op_sel_hi:[1,0]
	v_pk_mul_f32 v[24:25], v[24:25], v[140:141] op_sel_hi:[1,0]
	v_pk_mul_f32 v[22:23], v[22:23], v[140:141] op_sel_hi:[1,0]
	v_pk_mul_f32 v[20:21], v[20:21], v[140:141] op_sel_hi:[1,0]
	v_pk_mul_f32 v[18:19], v[18:19], v[140:141] op_sel_hi:[1,0]
	v_pk_mul_f32 v[16:17], v[16:17], v[140:141] op_sel_hi:[1,0]
	v_pk_mul_f32 v[14:15], v[14:15], v[140:141] op_sel_hi:[1,0]
	v_pk_mul_f32 v[12:13], v[12:13], v[140:141] op_sel_hi:[1,0]
	v_pk_mul_f32 v[10:11], v[10:11], v[140:141] op_sel_hi:[1,0]
	v_pk_mul_f32 v[8:9], v[8:9], v[140:141] op_sel_hi:[1,0]
	v_pk_mul_f32 v[6:7], v[6:7], v[140:141] op_sel_hi:[1,0]
	v_pk_mul_f32 v[4:5], v[4:5], v[140:141] op_sel_hi:[1,0]
	v_pk_add_f32 v[84:85], v[84:85], v[138:139] op_sel_hi:[1,0] neg_lo:[0,1] neg_hi:[0,1]
	v_pk_add_f32 v[70:71], v[70:71], v[138:139] op_sel_hi:[1,0] neg_lo:[0,1] neg_hi:[0,1]
	v_pk_add_f32 v[86:87], v[86:87], v[138:139] op_sel_hi:[1,0] neg_lo:[0,1] neg_hi:[0,1]
	v_pk_add_f32 v[72:73], v[72:73], v[138:139] op_sel_hi:[1,0] neg_lo:[0,1] neg_hi:[0,1]
	v_pk_add_f32 v[88:89], v[88:89], v[138:139] op_sel_hi:[1,0] neg_lo:[0,1] neg_hi:[0,1]
	v_pk_add_f32 v[74:75], v[74:75], v[138:139] op_sel_hi:[1,0] neg_lo:[0,1] neg_hi:[0,1]
	v_pk_add_f32 v[90:91], v[90:91], v[138:139] op_sel_hi:[1,0] neg_lo:[0,1] neg_hi:[0,1]
	v_pk_add_f32 v[76:77], v[76:77], v[138:139] op_sel_hi:[1,0] neg_lo:[0,1] neg_hi:[0,1]
	v_pk_add_f32 v[92:93], v[92:93], v[138:139] op_sel_hi:[1,0] neg_lo:[0,1] neg_hi:[0,1]
	v_pk_add_f32 v[78:79], v[78:79], v[138:139] op_sel_hi:[1,0] neg_lo:[0,1] neg_hi:[0,1]
	v_pk_add_f32 v[94:95], v[94:95], v[138:139] op_sel_hi:[1,0] neg_lo:[0,1] neg_hi:[0,1]
	v_pk_add_f32 v[80:81], v[80:81], v[138:139] op_sel_hi:[1,0] neg_lo:[0,1] neg_hi:[0,1]
	v_pk_add_f32 v[96:97], v[96:97], v[138:139] op_sel_hi:[1,0] neg_lo:[0,1] neg_hi:[0,1]
	v_pk_add_f32 v[82:83], v[82:83], v[138:139] op_sel_hi:[1,0] neg_lo:[0,1] neg_hi:[0,1]
	v_pk_add_f32 v[98:99], v[98:99], v[138:139] op_sel_hi:[1,0] neg_lo:[0,1] neg_hi:[0,1]
	s_andn2_b64 vcc, exec, s[46:47]
	s_cbranch_vccnz .LBB0_267

; #define LAS __attribute__((address_space(3)))
; #define MFMA32(a, b, c) __builtin_amdgcn_mfma_f32_32x32x16_bf16((a), (b), (c), 0, 0, 0)
; template <bool SUM> __device__ __forceinline__ bool softmax_tile(f32x16& pa, f32x16& pb, float& m, float& l, f32x16& o0, f32x16& o1, bool first) {
;     ...
; #pragma unroll
;     for (int r = 0; r < 16; ++r) { pa[r] = __builtin_amdgcn_exp2f(pa[r]); pb[r] = __builtin_amdgcn_exp2f(pb[r]); }
;     ...
;                 for (int ks = 0; ks < 4; ++ks) pf[mp][ks] = pack_frag(p[ks >> 1], ks & 1);
;             }
;             const LAS unsigned char* vb = bb + KB + r32 * VP + 8 * hi;
; #pragma unroll
;             for (int dh = 0; dh < 2; ++dh) {
;                 bf16x8 vf[4];
; #pragma unroll
;                 for (int ks = 0; ks < 4; ++ks) {
;                     const u32x2 v0 = *(const LAS u32x2*)(vb + dh * 32 * VP + 32 * ks), v1 = *(const LAS u32x2*)(vb + dh * 32 * VP + 32 * ks + 16);
;                     const u32x4 vv = {v0.x, v0.y, v1.x, v1.y}; vf[ks] = __builtin_bit_cast(bf16x8, vv); }
;                 __builtin_amdgcn_sched_barrier(0);
; #pragma unroll
;                 for (int ks = 0; ks < 4; ++ks)
; #pragma unroll
;                     for (int mp = 0; mp < NM; ++mp) o[mp][dh] = MFMA32(vf[ks], pf[mp][ks], o[mp][dh]);
;                 __builtin_amdgcn_sched_barrier(0);
;             }
;             if constexpr (MODE == 0) {
;                 const u32x4 o1 = {0x3f803f80u, 0x3f803f80u, 0x3f803f80u, 0x3f803f80u}; const bf16x8 ones = __builtin_bit_cast(bf16x8, o1);
; #pragma unroll
;                 for (int ks = 0; ks < 4; ++ks) lsum = MFMA32(ones, pf[0][ks], lsum);
;             }
;         }
;         if (it + 1 < NT) ATT_STORE((it + 1) & 1);
.LBB0_267:
	v_exp_f32_e32 v68, v68
	v_exp_f32_e32 v69, v69
	v_exp_f32_e32 v70, v70
	v_exp_f32_e32 v71, v71
	v_exp_f32_e32 v72, v72
	v_exp_f32_e32 v73, v73
	v_exp_f32_e32 v74, v74
	v_exp_f32_e32 v75, v75
	v_cvt_pk_bf16_f32 v68, v68, v69
	v_cvt_pk_bf16_f32 v69, v70, v71
	v_cvt_pk_bf16_f32 v70, v72, v73
	v_cvt_pk_bf16_f32 v71, v74, v75
	s_mov_b32 s70, s68
	s_mov_b32 s71, s68
	s_mov_b32 s69, s68
	v_mov_b64_e32 v[178:179], s[70:71]
	v_mov_b64_e32 v[176:177], s[68:69]
	v_mov_b32_e32 v208, v136
	s_waitcnt lgkmcnt(12)
	v_mfma_f32_32x32x16_bf16 v[4:19], v[144:147], v[68:71], v[4:19]
	v_exp_f32_e32 v76, v76
	v_exp_f32_e32 v77, v77
	v_exp_f32_e32 v78, v78
	v_mfma_f32_32x32x16_bf16 v[20:35], v[160:163], v[68:71], v[20:35]
	v_exp_f32_e32 v79, v79
	v_exp_f32_e32 v80, v80
	v_exp_f32_e32 v81, v81
	v_mfma_f32_32x32x16_bf16 v[36:51], v[176:179], v[68:71], v[36:51]
	v_exp_f32_e32 v82, v82
	v_exp_f32_e32 v83, v83
	v_cvt_pk_bf16_f32 v72, v76, v77
	v_cvt_pk_bf16_f32 v73, v78, v79
	v_cvt_pk_bf16_f32 v74, v80, v81
	v_cvt_pk_bf16_f32 v75, v82, v83
	s_waitcnt lgkmcnt(8)
	s_nop 0
	v_mfma_f32_32x32x16_bf16 v[4:19], v[148:151], v[72:75], v[4:19]
	v_exp_f32_e32 v84, v84
	v_exp_f32_e32 v85, v85
	v_exp_f32_e32 v86, v86
	v_mfma_f32_32x32x16_bf16 v[20:35], v[164:167], v[72:75], v[20:35]
	v_exp_f32_e32 v87, v87
	v_exp_f32_e32 v88, v88
	v_exp_f32_e32 v89, v89
	v_mfma_f32_32x32x16_bf16 v[36:51], v[176:179], v[72:75], v[36:51]
	v_exp_f32_e32 v90, v90
	v_exp_f32_e32 v91, v91
	v_cvt_pk_bf16_f32 v76, v84, v85
	v_cvt_pk_bf16_f32 v77, v86, v87
	v_cvt_pk_bf16_f32 v78, v88, v89
	v_cvt_pk_bf16_f32 v79, v90, v91
	s_waitcnt lgkmcnt(4)
	s_nop 0
	v_mfma_f32_32x32x16_bf16 v[4:19], v[152:155], v[76:79], v[4:19]
	v_exp_f32_e32 v92, v92
	v_exp_f32_e32 v93, v93
	v_exp_f32_e32 v94, v94
	v_mfma_f32_32x32x16_bf16 v[20:35], v[168:171], v[76:79], v[20:35]
	v_exp_f32_e32 v95, v95
	v_exp_f32_e32 v96, v96
	v_exp_f32_e32 v97, v97
	v_mfma_f32_32x32x16_bf16 v[36:51], v[176:179], v[76:79], v[36:51]
	v_exp_f32_e32 v98, v98
	v_exp_f32_e32 v99, v99
	v_cvt_pk_bf16_f32 v80, v92, v93
	v_cvt_pk_bf16_f32 v81, v94, v95
	v_cvt_pk_bf16_f32 v82, v96, v97
	v_cvt_pk_bf16_f32 v83, v98, v99
	s_waitcnt lgkmcnt(0)
	s_nop 0
	v_mfma_f32_32x32x16_bf16 v[4:19], v[156:159], v[80:83], v[4:19]
	v_mfma_f32_32x32x16_bf16 v[20:35], v[172:175], v[80:83], v[20:35]
	v_mfma_f32_32x32x16_bf16 v[36:51], v[176:179], v[80:83], v[36:51]
	s_bitcmp1_b32 s12, 0
	s_cselect_b32 s12, 0x5700, 0
	s_addk_i32 s12, 0x100
	v_add3_u32 v180, s12, v200, v201
	s_waitcnt vmcnt(0)
	ds_write_b128 v180, v[132:135]
	s_and_saveexec_b64 s[46:47], s[44:45]
	v_add3_u32 v180, s12, v203, v202
	ds_write_b128 v180, v[100:103] offset:128
	s_or_b64 exec, exec, s[46:47]
	s_mov_b64 s[18:19], 0x1000
	v_add_u32_e32 v180, s12, v210
	v_lshl_add_u64 v[194:195], v[194:195], 0, s[18:19]
	s_mov_b64 s[18:19], 0x10000
	v_add3_u32 v180, v180, v201, s13
	v_lshl_add_u64 v[0:1], v[0:1], 0, s[18:19]
	v_lshl_add_u64 v[196:197], v[196:197], 0, s[8:9]
	ds_write2_b64 v180, v[128:129], v[130:131] offset1:1
	s_cmp_lg_u32 s5, s11
	s_branch .Lmla_join
